# attention step loops: row-max exchange with lane^32 via v_permlane32_swap instead of ds_bpermute + lgkmcnt wait (6 sites, bitwise identical)
# baseline (speedup 1.0000x reference)
; template <int NA, int MG>
; __device__ __forceinline__ void attn_pair_unit(const Params& p, int l, int u, LAS unsigned char* pl, int sub, int lane, int& g, const bool own0, const int nu) {
;     ...
;         if (c + 1 < NS) { if (ATT_CVALID(c + 1)) ATT_DMA(c + 1, (g + 1) & 1); }
;         else if (nu >= 0) attn_prefetch0<NA>(p, nu, sub, lane, dl + ((g + 1) & 1) * VTILE);
;         bool use;
;         int cl = 0;
;         if (!NA) { cl = c - sub; use = ATT_CVALID(c) && cl >= 0 && cl <= 4; }
;         else { const int krow = R0 + c; use = (krow >= ua) && (krow <= ub); }
;         if (!use) continue;
;         const unsigned slot = (unsigned)(g & 1) * VTILE;
;         bf16x8 kf[8];
;         asm volatile("ds_read_b128 %0, %8 offset:0\n\tds_read_b128 %1, %8 offset:32\n\tds_read_b128 %2, %8 offset:64\n\tds_read_b128 %3, %8 offset:96\n\t"
;                      "ds_read_b128 %4, %8 offset:128\n\tds_read_b128 %5, %8 offset:160\n\tds_read_b128 %6, %8 offset:192\n\tds_read_b128 %7, %8 offset:224\n\t"
;                      "s_waitcnt lgkmcnt(0)"
;                      : "=&v"(kf[0]), "=&v"(kf[1]), "=&v"(kf[2]), "=&v"(kf[3]), "=&v"(kf[4]), "=&v"(kf[5]), "=&v"(kf[6]), "=&v"(kf[7])
;                      : "v"(plw + slot + koff) : "memory");
;         f32x16 s;
; #pragma unroll
;         for (int i = 0; i < 16; ++i) s[i] = 0.f;
; #pragma unroll
;         for (int kk = 0; kk < 8; ++kk) s = MFMA32(kf[kk], qf[kk], s);
;         float cm = -1e30f;
; #pragma unroll
;         for (int i = 0; i < 16; ++i) {
;             const int kr = (i & 3) + 8 * (i >> 2) + 4 * h;
;             bool valid; float sv = s[i];
;             if (!NA) { const int dj = 32 * cl + kr - r; valid = (dj >= 0) && (dj <= 128); if (cl >= 1 && cl <= 3) valid = true; }
;             else { const int krow = R0 + c, kcol = kstart + kr;
;                 valid = (krow >= rsq) && (krow < rsq + 8) && (kcol >= csq) && (kcol < csq + 16);
;                 const int ro = clampi(krow - iq + 7, 0, 14), co = clampi(kcol - cq + 15, 0, 30); sv += bl[ro * 31 + co]; }
;             sv = valid ? sv : -1e30f; s[i] = sv; cm = fmaxf(cm, sv);
;         }
;         cm = fmaxf(cm, __shfl_xor(cm, 32));
;         if (__builtin_amdgcn_ballot_w64(cm > m_run + 8.0f) != 0ull) {
;             const float m_new = fmaxf(m_run, cm), alpha = __builtin_amdgcn_exp2f(m_run - m_new);
;             l_run *= alpha; m_run = m_new;
; #pragma unroll
.LBB0_156:
	s_sub_i32 s50, s64, 64
	s_cmp_lt_i32 s50, 0
	s_cbranch_scc1 .LBB0_161
	s_cmp_lt_i32 s50, s82
	s_cselect_b64 s[64:65], -1, 0
	s_cmp_lt_u32 s86, 5
	s_cselect_b64 s[96:97], -1, 0
	s_and_b64 s[64:65], s[64:65], s[96:97]
	s_andn2_b64 vcc, exec, s[64:65]
	s_cbranch_vccnz .LBB0_161
	s_bitcmp1_b32 s93, 0
	s_cselect_b32 s50, 0x2100, 0
	s_add_i32 s50, s50, s67
	v_add_u32_e32 v70, s50, v166
	ds_read_b128 v[66:69], v70 offset:0
	ds_read_b128 v[140:143], v70 offset:32
	ds_read_b128 v[184:187], v70 offset:64
	ds_read_b128 v[188:191], v70 offset:96
	ds_read_b128 v[192:195], v70 offset:128
	ds_read_b128 v[196:199], v70 offset:160
	ds_read_b128 v[210:213], v70 offset:192
	ds_read_b128 v[214:217], v70 offset:224
	s_waitcnt lgkmcnt(0)
	s_add_i32 s64, s86, -1
	v_mfma_f32_32x32x16_bf16 v[66:81], v[66:69], v[110:113], 0
	v_add_u32_e32 v139, s85, v135
	s_cmp_lt_u32 s64, 3
	s_cselect_b64 s[64:65], -1, 0
	v_cmp_gt_u32_e32 vcc, s33, v139
	s_or_b64 vcc, s[64:65], vcc
	v_add_u32_e32 v133, 1, v139
	v_mfma_f32_32x32x16_bf16 v[66:81], v[140:143], v[106:109], v[66:81]
	v_add_u32_e32 v140, 2, v139
	v_mfma_f32_32x32x16_bf16 v[66:81], v[184:187], v[102:105], v[66:81]
	v_mfma_f32_32x32x16_bf16 v[66:81], v[188:191], v[98:101], v[66:81]
	v_mfma_f32_32x32x16_bf16 v[66:81], v[192:195], v[94:97], v[66:81]
	v_mfma_f32_32x32x16_bf16 v[66:81], v[196:199], v[90:93], v[66:81]
	v_mfma_f32_32x32x16_bf16 v[66:81], v[210:213], v[86:89], v[66:81]
	v_mfma_f32_32x32x16_bf16 v[66:81], v[214:217], v[82:85], v[66:81]
	s_nop 11
	v_cndmask_b32_e32 v66, v206, v66, vcc
	v_cmp_gt_u32_e32 vcc, s33, v133
	s_or_b64 vcc, s[64:65], vcc
	s_nop 0
	v_cndmask_b32_e32 v67, v206, v67, vcc
	v_cmp_gt_u32_e32 vcc, s33, v140
	s_or_b64 vcc, s[64:65], vcc
	v_add_u32_e32 v140, 3, v139
	v_cndmask_b32_e32 v68, v206, v68, vcc
	v_cmp_gt_u32_e32 vcc, s33, v140
	s_or_b64 vcc, s[64:65], vcc
	v_add_u32_e32 v140, 8, v139
	v_cndmask_b32_e32 v69, v206, v69, vcc
	v_cmp_gt_u32_e32 vcc, s33, v140
	s_or_b64 vcc, s[64:65], vcc
	v_add_u32_e32 v140, 9, v139
	v_cndmask_b32_e32 v70, v206, v70, vcc
	v_cmp_gt_u32_e32 vcc, s33, v140
	v_max3_f32 v133, v66, s46, v67
	s_or_b64 vcc, s[64:65], vcc
	v_max3_f32 v133, v133, v68, v69
	v_cndmask_b32_e32 v71, v206, v71, vcc
	v_max3_f32 v140, v133, v70, v71
	v_add_u32_e32 v133, 10, v139
	v_cmp_gt_u32_e32 vcc, s33, v133
	s_or_b64 vcc, s[64:65], vcc
	v_add_u32_e32 v133, 11, v139
	v_cndmask_b32_e32 v72, v206, v72, vcc
	v_cmp_gt_u32_e32 vcc, s33, v133
	s_or_b64 vcc, s[64:65], vcc
	s_nop 0
	v_cndmask_b32_e32 v133, v206, v73, vcc
	v_add_u32_e32 v73, 16, v139
	v_cmp_gt_u32_e32 vcc, s33, v73
	s_or_b64 vcc, s[64:65], vcc
	v_max3_f32 v140, v140, v72, v133
	v_cndmask_b32_e32 v73, v206, v74, vcc
	v_add_u32_e32 v74, 17, v139
	v_cmp_gt_u32_e32 vcc, s33, v74
	s_or_b64 vcc, s[64:65], vcc
	s_nop 0
	v_cndmask_b32_e32 v74, v206, v75, vcc
	v_add_u32_e32 v75, 18, v139
	v_cmp_gt_u32_e32 vcc, s33, v75
	s_or_b64 vcc, s[64:65], vcc
	v_max3_f32 v140, v140, v73, v74
	v_cndmask_b32_e32 v75, v206, v76, vcc
	v_add_u32_e32 v76, 19, v139
	v_cmp_gt_u32_e32 vcc, s33, v76
	s_or_b64 vcc, s[64:65], vcc
	s_nop 0
	v_cndmask_b32_e32 v76, v206, v77, vcc
	v_add_u32_e32 v77, 24, v139
	v_cmp_gt_u32_e32 vcc, s33, v77
	s_or_b64 vcc, s[64:65], vcc
	v_max3_f32 v140, v140, v75, v76
	v_cndmask_b32_e32 v77, v206, v78, vcc
	v_add_u32_e32 v78, 25, v139
	v_cmp_gt_u32_e32 vcc, s33, v78
	s_or_b64 vcc, s[64:65], vcc
	s_nop 0
	v_cndmask_b32_e32 v78, v206, v79, vcc
	v_add_u32_e32 v79, 26, v139
	v_cmp_gt_u32_e32 vcc, s33, v79
	s_or_b64 vcc, s[64:65], vcc
	v_max3_f32 v140, v140, v77, v78
	v_cndmask_b32_e32 v79, v206, v80, vcc
	v_add_u32_e32 v80, 27, v139
	v_cmp_gt_u32_e32 vcc, s33, v80
	s_or_b64 vcc, s[64:65], vcc
	v_xor_b32_e32 v139, 32, v204
	v_cndmask_b32_e32 v80, v206, v81, vcc
	v_max3_f32 v81, v140, v79, v80
	v_and_b32_e32 v140, 64, v204
	v_add_u32_e32 v140, 64, v140
	v_cmp_lt_i32_e32 vcc, v139, v140
	s_nop 1
	v_mov_b32_e32 v139, v81
	v_mov_b32_e32 v240, v81
	s_nop 1
	v_permlane32_swap_b32_e32 v139, v240
	v_max_f32_e32 v81, v139, v240
	v_add_f32_e32 v139, 0x41000000, v122
	v_cmp_gt_f32_e32 vcc, v81, v139
	s_cbranch_vccz .LBB0_160
	v_max_f32_e32 v81, v81, v81
	v_max_f32_e32 v139, v122, v122
	v_max_f32_e32 v81, v139, v81
	v_sub_f32_e32 v122, v122, v81
	v_exp_f32_e32 v122, v122
	s_nop 0
	v_pk_mul_f32 v[64:65], v[64:65], v[122:123] op_sel_hi:[1,0]
	v_pk_mul_f32 v[62:63], v[62:63], v[122:123] op_sel_hi:[1,0]
	v_pk_mul_f32 v[60:61], v[60:61], v[122:123] op_sel_hi:[1,0]
	v_pk_mul_f32 v[58:59], v[58:59], v[122:123] op_sel_hi:[1,0]
	v_pk_mul_f32 v[56:57], v[56:57], v[122:123] op_sel_hi:[1,0]
	v_pk_mul_f32 v[54:55], v[54:55], v[122:123] op_sel_hi:[1,0]
	v_pk_mul_f32 v[52:53], v[52:53], v[122:123] op_sel_hi:[1,0]
	v_pk_mul_f32 v[50:51], v[50:51], v[122:123] op_sel_hi:[1,0]
	v_pk_mul_f32 v[48:49], v[48:49], v[122:123] op_sel_hi:[1,0]
	v_pk_mul_f32 v[46:47], v[46:47], v[122:123] op_sel_hi:[1,0]
	v_pk_mul_f32 v[44:45], v[44:45], v[122:123] op_sel_hi:[1,0]
	v_pk_mul_f32 v[42:43], v[42:43], v[122:123] op_sel_hi:[1,0]
	v_pk_mul_f32 v[40:41], v[40:41], v[122:123] op_sel_hi:[1,0]
	v_pk_mul_f32 v[38:39], v[38:39], v[122:123] op_sel_hi:[1,0]
	v_pk_mul_f32 v[36:37], v[36:37], v[122:123] op_sel_hi:[1,0]
	v_pk_mul_f32 v[34:35], v[34:35], v[122:123] op_sel_hi:[1,0]
	v_pk_mul_f32 v[32:33], v[32:33], v[122:123] op_sel_hi:[1,0]
	v_pk_mul_f32 v[30:31], v[30:31], v[122:123] op_sel_hi:[1,0]
	v_pk_mul_f32 v[28:29], v[28:29], v[122:123] op_sel_hi:[1,0]
	v_pk_mul_f32 v[26:27], v[26:27], v[122:123] op_sel_hi:[1,0]
	v_pk_mul_f32 v[24:25], v[24:25], v[122:123] op_sel_hi:[1,0]
	v_pk_mul_f32 v[22:23], v[22:23], v[122:123] op_sel_hi:[1,0]
	v_pk_mul_f32 v[20:21], v[20:21], v[122:123] op_sel_hi:[1,0]
	v_pk_mul_f32 v[18:19], v[18:19], v[122:123] op_sel_hi:[1,0]
	v_pk_mul_f32 v[16:17], v[16:17], v[122:123] op_sel_hi:[1,0]
	v_pk_mul_f32 v[14:15], v[14:15], v[122:123] op_sel_hi:[1,0]
	v_pk_mul_f32 v[12:13], v[12:13], v[122:123] op_sel_hi:[1,0]
	v_pk_mul_f32 v[10:11], v[10:11], v[122:123] op_sel_hi:[1,0]
	v_pk_mul_f32 v[8:9], v[8:9], v[122:123] op_sel_hi:[1,0]
	v_pk_mul_f32 v[6:7], v[6:7], v[122:123] op_sel_hi:[1,0]
	v_pk_mul_f32 v[4:5], v[4:5], v[122:123] op_sel_hi:[1,0]
	v_pk_mul_f32 v[2:3], v[2:3], v[122:123] op_sel_hi:[1,0]
	v_mul_f32_e32 v123, v123, v122
	v_mov_b32_e32 v122, v81

; template <int NA, int MG>
; __device__ __forceinline__ void attn_pair_unit(const Params& p, int l, int u, LAS unsigned char* pl, int sub, int lane, int& g, const bool own0, const int nu) {
;     ...
;         if (c + 1 < NS) { if (ATT_CVALID(c + 1)) ATT_DMA(c + 1, (g + 1) & 1); }
;         else if (nu >= 0) attn_prefetch0<NA>(p, nu, sub, lane, dl + ((g + 1) & 1) * VTILE);
;         bool use;
;         int cl = 0;
;         if (!NA) { cl = c - sub; use = ATT_CVALID(c) && cl >= 0 && cl <= 4; }
;         else { const int krow = R0 + c; use = (krow >= ua) && (krow <= ub); }
;         if (!use) continue;
;         const unsigned slot = (unsigned)(g & 1) * VTILE;
;         bf16x8 kf[8];
;         asm volatile("ds_read_b128 %0, %8 offset:0\n\tds_read_b128 %1, %8 offset:32\n\tds_read_b128 %2, %8 offset:64\n\tds_read_b128 %3, %8 offset:96\n\t"
;                      "ds_read_b128 %4, %8 offset:128\n\tds_read_b128 %5, %8 offset:160\n\tds_read_b128 %6, %8 offset:192\n\tds_read_b128 %7, %8 offset:224\n\t"
;                      "s_waitcnt lgkmcnt(0)"
;                      : "=&v"(kf[0]), "=&v"(kf[1]), "=&v"(kf[2]), "=&v"(kf[3]), "=&v"(kf[4]), "=&v"(kf[5]), "=&v"(kf[6]), "=&v"(kf[7])
;                      : "v"(plw + slot + koff) : "memory");
;         f32x16 s;
; #pragma unroll
;         for (int i = 0; i < 16; ++i) s[i] = 0.f;
; #pragma unroll
;         for (int kk = 0; kk < 8; ++kk) s = MFMA32(kf[kk], qf[kk], s);
;         float cm = -1e30f;
; #pragma unroll
;         for (int i = 0; i < 16; ++i) {
;             const int kr = (i & 3) + 8 * (i >> 2) + 4 * h;
;             bool valid; float sv = s[i];
;             if (!NA) { const int dj = 32 * cl + kr - r; valid = (dj >= 0) && (dj <= 128); if (cl >= 1 && cl <= 3) valid = true; }
;             else { const int krow = R0 + c, kcol = kstart + kr;
;                 valid = (krow >= rsq) && (krow < rsq + 8) && (kcol >= csq) && (kcol < csq + 16);
;                 const int ro = clampi(krow - iq + 7, 0, 14), co = clampi(kcol - cq + 15, 0, 30); sv += bl[ro * 31 + co]; }
;             sv = valid ? sv : -1e30f; s[i] = sv; cm = fmaxf(cm, sv);
;         }
;         cm = fmaxf(cm, __shfl_xor(cm, 32));
;         if (__builtin_amdgcn_ballot_w64(cm > m_run + 8.0f) != 0ull) {
;             const float m_new = fmaxf(m_run, cm), alpha = __builtin_amdgcn_exp2f(m_run - m_new);
;             l_run *= alpha; m_run = m_new;
; #pragma unroll
.LBB0_165:
	s_add_i32 s2, s66, 0x60
	s_cmp_lt_u32 s2, s82
	s_cselect_b64 s[2:3], -1, 0
	s_and_b64 s[2:3], s[2:3], s[94:95]
	s_andn2_b64 vcc, exec, s[2:3]
	s_cbranch_vccnz .LBB0_169
	s_bitcmp1_b32 s64, 0
	s_cselect_b32 s2, 0x2100, 0
	s_add_i32 s2, s2, s67
	v_add_u32_e32 v70, s2, v166
	ds_read_b128 v[66:69], v70 offset:0
	ds_read_b128 v[140:143], v70 offset:32
	ds_read_b128 v[184:187], v70 offset:64
	ds_read_b128 v[188:191], v70 offset:96
	ds_read_b128 v[192:195], v70 offset:128
	ds_read_b128 v[196:199], v70 offset:160
	ds_read_b128 v[210:213], v70 offset:192
	ds_read_b128 v[214:217], v70 offset:224
	s_waitcnt lgkmcnt(0)
	s_nop 0
	v_mfma_f32_32x32x16_bf16 v[66:81], v[66:69], v[110:113], 0
	v_mfma_f32_32x32x16_bf16 v[66:81], v[140:143], v[106:109], v[66:81]
	v_mfma_f32_32x32x16_bf16 v[66:81], v[184:187], v[102:105], v[66:81]
	v_mfma_f32_32x32x16_bf16 v[66:81], v[188:191], v[98:101], v[66:81]
	v_mfma_f32_32x32x16_bf16 v[66:81], v[192:195], v[94:97], v[66:81]
	v_mfma_f32_32x32x16_bf16 v[66:81], v[196:199], v[90:93], v[66:81]
	v_mfma_f32_32x32x16_bf16 v[66:81], v[210:213], v[86:89], v[66:81]
	v_and_b32_e32 v87, 64, v204
	v_xor_b32_e32 v86, 32, v204
	v_add_u32_e32 v87, 64, v87
	v_cmp_lt_i32_e32 vcc, v86, v87
	s_nop 1
	v_cndmask_b32_e32 v86, v204, v86, vcc
	v_mfma_f32_32x32x16_bf16 v[66:81], v[214:217], v[82:85], v[66:81]
	v_lshlrev_b32_e32 v90, 2, v86
	s_nop 10
	v_cndmask_b32_e64 v89, v206, v66, s[6:7]
	v_cndmask_b32_e64 v88, v206, v67, s[8:9]
	v_cndmask_b32_e64 v87, v206, v68, s[10:11]
	v_cndmask_b32_e64 v86, v206, v69, s[12:13]
	v_cndmask_b32_e64 v82, v206, v73, s[20:21]
	v_cndmask_b32_e64 v73, v206, v74, s[22:23]
	v_max3_f32 v74, v89, s46, v88
	v_cndmask_b32_e64 v85, v206, v70, s[14:15]
	v_cndmask_b32_e64 v84, v206, v71, s[16:17]
	v_max3_f32 v74, v74, v87, v86
	v_cndmask_b32_e64 v83, v206, v72, s[18:19]
	v_max3_f32 v74, v74, v85, v84
	v_cndmask_b32_e64 v72, v206, v75, s[24:25]
	v_max3_f32 v74, v74, v83, v82
	v_cndmask_b32_e64 v71, v206, v76, s[26:27]
	v_cndmask_b32_e64 v70, v206, v77, s[28:29]
	v_max3_f32 v74, v74, v73, v72
	v_cndmask_b32_e64 v69, v206, v78, s[30:31]
	v_cndmask_b32_e64 v68, v206, v79, s[34:35]
	v_max3_f32 v74, v74, v71, v70
	v_cndmask_b32_e64 v67, v206, v80, s[36:37]
	v_cndmask_b32_e64 v66, v206, v81, s[38:39]
	v_max3_f32 v74, v74, v69, v68
	v_max3_f32 v74, v74, v67, v66
	v_mov_b32_e32 v75, v74
	v_mov_b32_e32 v240, v74
	s_nop 1
	v_permlane32_swap_b32_e32 v75, v240
	v_max_f32_e32 v74, v75, v240
	v_add_f32_e32 v75, 0x41000000, v122
	v_cmp_gt_f32_e32 vcc, v74, v75
	s_cbranch_vccz .LBB0_168
	v_max_f32_e32 v74, v74, v74
	v_max_f32_e32 v75, v122, v122
	v_max_f32_e32 v75, v75, v74
	v_sub_f32_e32 v74, v122, v75
	v_exp_f32_e32 v74, v74
	v_mov_b32_e32 v122, v75
	v_pk_mul_f32 v[64:65], v[64:65], v[74:75] op_sel_hi:[1,0]
	v_pk_mul_f32 v[62:63], v[62:63], v[74:75] op_sel_hi:[1,0]
	v_pk_mul_f32 v[60:61], v[60:61], v[74:75] op_sel_hi:[1,0]
	v_pk_mul_f32 v[58:59], v[58:59], v[74:75] op_sel_hi:[1,0]
	v_pk_mul_f32 v[56:57], v[56:57], v[74:75] op_sel_hi:[1,0]
	v_pk_mul_f32 v[54:55], v[54:55], v[74:75] op_sel_hi:[1,0]
	v_pk_mul_f32 v[52:53], v[52:53], v[74:75] op_sel_hi:[1,0]
	v_pk_mul_f32 v[50:51], v[50:51], v[74:75] op_sel_hi:[1,0]
	v_pk_mul_f32 v[48:49], v[48:49], v[74:75] op_sel_hi:[1,0]
	v_pk_mul_f32 v[46:47], v[46:47], v[74:75] op_sel_hi:[1,0]
	v_pk_mul_f32 v[44:45], v[44:45], v[74:75] op_sel_hi:[1,0]
	v_pk_mul_f32 v[42:43], v[42:43], v[74:75] op_sel_hi:[1,0]
	v_pk_mul_f32 v[40:41], v[40:41], v[74:75] op_sel_hi:[1,0]
	v_pk_mul_f32 v[38:39], v[38:39], v[74:75] op_sel_hi:[1,0]
	v_pk_mul_f32 v[36:37], v[36:37], v[74:75] op_sel_hi:[1,0]
	v_pk_mul_f32 v[34:35], v[34:35], v[74:75] op_sel_hi:[1,0]
	v_pk_mul_f32 v[32:33], v[32:33], v[74:75] op_sel_hi:[1,0]
	v_pk_mul_f32 v[30:31], v[30:31], v[74:75] op_sel_hi:[1,0]
	v_pk_mul_f32 v[28:29], v[28:29], v[74:75] op_sel_hi:[1,0]
	v_pk_mul_f32 v[26:27], v[26:27], v[74:75] op_sel_hi:[1,0]
	v_pk_mul_f32 v[24:25], v[24:25], v[74:75] op_sel_hi:[1,0]
	v_pk_mul_f32 v[22:23], v[22:23], v[74:75] op_sel_hi:[1,0]
	v_pk_mul_f32 v[20:21], v[20:21], v[74:75] op_sel_hi:[1,0]
	v_pk_mul_f32 v[18:19], v[18:19], v[74:75] op_sel_hi:[1,0]
	v_pk_mul_f32 v[16:17], v[16:17], v[74:75] op_sel_hi:[1,0]
	v_pk_mul_f32 v[14:15], v[14:15], v[74:75] op_sel_hi:[1,0]
	v_pk_mul_f32 v[12:13], v[12:13], v[74:75] op_sel_hi:[1,0]
	v_pk_mul_f32 v[10:11], v[10:11], v[74:75] op_sel_hi:[1,0]
	v_pk_mul_f32 v[8:9], v[8:9], v[74:75] op_sel_hi:[1,0]
	v_pk_mul_f32 v[6:7], v[6:7], v[74:75] op_sel_hi:[1,0]
	v_pk_mul_f32 v[4:5], v[4:5], v[74:75] op_sel_hi:[1,0]
	v_pk_mul_f32 v[2:3], v[2:3], v[74:75] op_sel_hi:[1,0]
	v_mul_f32_e32 v123, v123, v74

; #define MFMA32(a, b, c) __builtin_amdgcn_mfma_f32_32x32x16_bf16((a), (b), (c), 0, 0, 0)
; template <int NA, int MG>
; __device__ __forceinline__ void attn_pair_unit(const Params& p, int l, int u, LAS unsigned char* pl, int sub, int lane, int& g, const bool own0, const int nu) {
;     ...
;         else { const int krow = R0 + c; use = (krow >= ua) && (krow <= ub); }
;         if (!use) continue;
;         const unsigned slot = (unsigned)(g & 1) * VTILE;
;         bf16x8 kf[8];
;         asm volatile("ds_read_b128 %0, %8 offset:0\n\tds_read_b128 %1, %8 offset:32\n\tds_read_b128 %2, %8 offset:64\n\tds_read_b128 %3, %8 offset:96\n\t"
;                      "ds_read_b128 %4, %8 offset:128\n\tds_read_b128 %5, %8 offset:160\n\tds_read_b128 %6, %8 offset:192\n\tds_read_b128 %7, %8 offset:224\n\t"
;                      "s_waitcnt lgkmcnt(0)"
;                      : "=&v"(kf[0]), "=&v"(kf[1]), "=&v"(kf[2]), "=&v"(kf[3]), "=&v"(kf[4]), "=&v"(kf[5]), "=&v"(kf[6]), "=&v"(kf[7])
;                      : "v"(plw + slot + koff) : "memory");
;         f32x16 s;
; #pragma unroll
;         for (int i = 0; i < 16; ++i) s[i] = 0.f;
; #pragma unroll
;         for (int kk = 0; kk < 8; ++kk) s = MFMA32(kf[kk], qf[kk], s);
;         float cm = -1e30f;
; #pragma unroll
;         for (int i = 0; i < 16; ++i) {
;             const int kr = (i & 3) + 8 * (i >> 2) + 4 * h;
;             bool valid; float sv = s[i];
;             if (!NA) { const int dj = 32 * cl + kr - r; valid = (dj >= 0) && (dj <= 128); if (cl >= 1 && cl <= 3) valid = true; }
;             else { const int krow = R0 + c, kcol = kstart + kr;
;                 valid = (krow >= rsq) && (krow < rsq + 8) && (kcol >= csq) && (kcol < csq + 16);
;                 const int ro = clampi(krow - iq + 7, 0, 14), co = clampi(kcol - cq + 15, 0, 30); sv += bl[ro * 31 + co]; }
;             sv = valid ? sv : -1e30f; s[i] = sv; cm = fmaxf(cm, sv);
;         }
;         cm = fmaxf(cm, __shfl_xor(cm, 32));
.LBB0_184:
	s_add_i32 s13, s13, -4
	s_cmp_le_u32 s66, s13
	s_cselect_b64 s[42:43], -1, 0
	s_or_b64 s[42:43], s[52:53], s[42:43]
	s_cmp_le_u32 s13, s6
	s_cselect_b64 vcc, -1, 0
	s_and_b64 s[42:43], s[42:43], vcc
	s_andn2_b64 vcc, exec, s[42:43]
	s_cbranch_vccnz .LBB0_181
	s_bitcmp1_b32 s12, 0
	s_cselect_b32 s12, 0x2100, 0
	s_add_i32 s12, s12, s67
	v_add_u32_e32 v0, s12, v166
	ds_read_b128 v[2:5], v0 offset:0
	ds_read_b128 v[6:9], v0 offset:32
	ds_read_b128 v[10:13], v0 offset:64
	ds_read_b128 v[234:237], v0 offset:96
	ds_read_b128 v[238:241], v0 offset:128
	ds_read_b128 v[242:245], v0 offset:160
	ds_read_b128 v[246:249], v0 offset:192
	ds_read_b128 v[250:253], v0 offset:224
	s_waitcnt lgkmcnt(0)
	v_add_u32_e32 v0, s11, v226
	v_mfma_f32_32x32x16_bf16 v[80:95], v[2:5], v[124:127], 0
	v_add_u32_e32 v2, -4, v0
	v_add_u32_e32 v0, 3, v0
	v_cmp_ge_u32_e32 vcc, s13, v183
	v_cmp_lt_u32_e64 s[42:43], s13, v184
	v_min_u32_e32 v0, 14, v0
	s_and_b64 s[42:43], vcc, s[42:43]
	v_mul_u32_u24_e32 v0, 0x7c, v0
	v_mfma_f32_32x32x16_bf16 v[80:95], v[6:9], v[120:123], v[80:95]
	v_cmp_lt_i32_e32 vcc, -8, v2
	s_nop 1
	v_cndmask_b32_e32 v0, 0, v0, vcc
	v_add_u32_e32 v0, s67, v0
	v_lshl_add_u32 v2, v185, 2, v0
	v_lshl_add_u32 v3, v186, 2, v0
	v_mfma_f32_32x32x16_bf16 v[80:95], v[10:13], v[116:119], v[80:95]
	v_lshl_add_u32 v4, v187, 2, v0
	v_lshl_add_u32 v5, v188, 2, v0
	v_lshl_add_u32 v6, v189, 2, v0
	v_lshl_add_u32 v7, v190, 2, v0
	v_lshl_add_u32 v8, v191, 2, v0
	v_lshl_add_u32 v9, v192, 2, v0
	v_lshl_add_u32 v10, v193, 2, v0
	v_mfma_f32_32x32x16_bf16 v[80:95], v[234:237], v[112:115], v[80:95]
	v_lshl_add_u32 v11, v194, 2, v0
	v_lshl_add_u32 v12, v195, 2, v0
	v_lshl_add_u32 v15, v196, 2, v0
	v_lshl_add_u32 v233, v197, 2, v0
	v_lshl_add_u32 v234, v198, 2, v0
	v_lshl_add_u32 v235, v199, 2, v0
	v_lshl_add_u32 v236, v200, 2, v0
	v_mfma_f32_32x32x16_bf16 v[80:95], v[238:241], v[104:107], v[80:95]
	ds_read_b32 v0, v2 offset:33792
	ds_read_b32 v2, v3 offset:33792
	ds_read_b32 v3, v4 offset:33792
	ds_read_b32 v4, v5 offset:33792
	ds_read_b32 v5, v6 offset:33792
	ds_read_b32 v6, v7 offset:33792
	ds_read_b32 v7, v8 offset:33792
	ds_read_b32 v8, v9 offset:33792
	s_and_b64 vcc, s[42:43], s[94:95]
	v_mfma_f32_32x32x16_bf16 v[80:95], v[242:245], v[108:111], v[80:95]
	v_mfma_f32_32x32x16_bf16 v[80:95], v[246:249], v[100:103], v[80:95]
	v_mfma_f32_32x32x16_bf16 v[80:95], v[250:253], v[96:99], v[80:95]
	s_waitcnt lgkmcnt(0)
	s_nop 10
	v_add_f32_e32 v0, v80, v0
	v_add_f32_e32 v2, v81, v2
	v_cndmask_b32_e32 v80, v206, v0, vcc
	s_and_b64 vcc, s[42:43], s[40:41]
	v_add_f32_e32 v3, v82, v3
	v_cndmask_b32_e32 v13, v206, v2, vcc
	s_and_b64 vcc, s[42:43], s[64:65]
	v_add_f32_e32 v4, v83, v4
	v_cndmask_b32_e32 v14, v206, v3, vcc
	s_and_b64 vcc, s[42:43], s[70:71]
	v_add_f32_e32 v9, v84, v5
	v_cndmask_b32_e32 v5, v206, v4, vcc
	s_and_b64 vcc, s[42:43], s[72:73]
	v_add_f32_e32 v6, v85, v6
	v_cndmask_b32_e32 v4, v206, v9, vcc
	s_and_b64 vcc, s[42:43], s[74:75]
	v_add_f32_e32 v7, v86, v7
	v_cndmask_b32_e32 v3, v206, v6, vcc
	s_and_b64 vcc, s[42:43], s[76:77]
	v_add_f32_e32 v8, v87, v8
	v_cndmask_b32_e32 v2, v206, v7, vcc
	s_and_b64 vcc, s[42:43], s[78:79]
	v_cndmask_b32_e32 v0, v206, v8, vcc
	ds_read_b32 v7, v10 offset:33792
	ds_read_b32 v8, v11 offset:33792
	ds_read_b32 v9, v12 offset:33792
	ds_read_b32 v10, v15 offset:33792
	ds_read_b32 v81, v233 offset:33792
	ds_read_b32 v82, v234 offset:33792
	ds_read_b32 v83, v235 offset:33792
	ds_read_b32 v84, v236 offset:33792
	s_waitcnt lgkmcnt(0)
	v_add_f32_e32 v7, v88, v7
	s_and_b64 vcc, s[42:43], s[82:83]
	v_max3_f32 v6, v80, s46, v13
	v_cndmask_b32_e32 v15, v206, v7, vcc
	v_add_f32_e32 v7, v89, v8
	s_and_b64 vcc, s[42:43], s[84:85]
	v_max3_f32 v6, v6, v14, v5
	v_cndmask_b32_e32 v11, v206, v7, vcc
	v_add_f32_e32 v7, v90, v9
	s_and_b64 vcc, s[42:43], s[86:87]
	v_max3_f32 v6, v6, v4, v3
	v_cndmask_b32_e32 v12, v206, v7, vcc
	v_add_f32_e32 v7, v91, v10
	s_and_b64 vcc, s[42:43], s[96:97]
	v_max3_f32 v6, v6, v2, v0
	v_cndmask_b32_e32 v9, v206, v7, vcc
	v_add_f32_e32 v7, v92, v81
	s_and_b64 vcc, s[42:43], s[44:45]
	v_max3_f32 v6, v6, v15, v11
	v_cndmask_b32_e32 v10, v206, v7, vcc
	v_add_f32_e32 v7, v93, v82
	s_and_b64 vcc, s[42:43], s[48:49]
	v_max3_f32 v6, v6, v12, v9
	v_cndmask_b32_e32 v7, v206, v7, vcc
	v_max3_f32 v81, v6, v10, v7
	v_add_f32_e32 v6, v94, v83
	s_and_b64 vcc, s[42:43], s[2:3]
	v_cndmask_b32_e32 v8, v206, v6, vcc
	v_add_f32_e32 v6, v95, v84
	s_and_b64 vcc, s[42:43], s[54:55]
	v_cndmask_b32_e32 v6, v206, v6, vcc
	v_max3_f32 v81, v81, v8, v6
	v_mov_b32_e32 v82, v81
	v_mov_b32_e32 v84, v81
	s_nop 1
	v_permlane32_swap_b32_e32 v82, v84
	v_max_f32_e32 v81, v82, v84
	v_add_f32_e32 v82, 0x41000000, v232
	v_cmp_gt_f32_e32 vcc, v81, v82
	s_cbranch_vccz .LBB0_180
	v_max_f32_e32 v81, v81, v81
	v_max_f32_e32 v82, v232, v232
	v_max_f32_e32 v81, v82, v81
	v_sub_f32_e32 v82, v232, v81
	v_exp_f32_e32 v82, v82
	v_mov_b32_e32 v232, v81
	v_pk_mul_f32 v[78:79], v[78:79], v[82:83] op_sel_hi:[1,0]
	v_pk_mul_f32 v[76:77], v[76:77], v[82:83] op_sel_hi:[1,0]
	v_pk_mul_f32 v[74:75], v[74:75], v[82:83] op_sel_hi:[1,0]
	v_pk_mul_f32 v[72:73], v[72:73], v[82:83] op_sel_hi:[1,0]
	v_pk_mul_f32 v[70:71], v[70:71], v[82:83] op_sel_hi:[1,0]
	v_pk_mul_f32 v[68:69], v[68:69], v[82:83] op_sel_hi:[1,0]
	v_pk_mul_f32 v[66:67], v[66:67], v[82:83] op_sel_hi:[1,0]
	v_pk_mul_f32 v[64:65], v[64:65], v[82:83] op_sel_hi:[1,0]
	v_pk_mul_f32 v[62:63], v[62:63], v[82:83] op_sel_hi:[1,0]
	v_pk_mul_f32 v[60:61], v[60:61], v[82:83] op_sel_hi:[1,0]
	v_pk_mul_f32 v[58:59], v[58:59], v[82:83] op_sel_hi:[1,0]
	v_pk_mul_f32 v[56:57], v[56:57], v[82:83] op_sel_hi:[1,0]
	v_pk_mul_f32 v[54:55], v[54:55], v[82:83] op_sel_hi:[1,0]
	v_pk_mul_f32 v[52:53], v[52:53], v[82:83] op_sel_hi:[1,0]
	v_pk_mul_f32 v[50:51], v[50:51], v[82:83] op_sel_hi:[1,0]
	v_pk_mul_f32 v[48:49], v[48:49], v[82:83] op_sel_hi:[1,0]
	v_pk_mul_f32 v[46:47], v[46:47], v[82:83] op_sel_hi:[1,0]
	v_pk_mul_f32 v[44:45], v[44:45], v[82:83] op_sel_hi:[1,0]
	v_pk_mul_f32 v[42:43], v[42:43], v[82:83] op_sel_hi:[1,0]
	v_pk_mul_f32 v[40:41], v[40:41], v[82:83] op_sel_hi:[1,0]
	v_pk_mul_f32 v[38:39], v[38:39], v[82:83] op_sel_hi:[1,0]
	v_pk_mul_f32 v[36:37], v[36:37], v[82:83] op_sel_hi:[1,0]
	v_pk_mul_f32 v[34:35], v[34:35], v[82:83] op_sel_hi:[1,0]
	v_pk_mul_f32 v[32:33], v[32:33], v[82:83] op_sel_hi:[1,0]
	v_pk_mul_f32 v[30:31], v[30:31], v[82:83] op_sel_hi:[1,0]
	v_pk_mul_f32 v[28:29], v[28:29], v[82:83] op_sel_hi:[1,0]
	v_pk_mul_f32 v[26:27], v[26:27], v[82:83] op_sel_hi:[1,0]
	v_pk_mul_f32 v[24:25], v[24:25], v[82:83] op_sel_hi:[1,0]
	v_pk_mul_f32 v[22:23], v[22:23], v[82:83] op_sel_hi:[1,0]
	v_pk_mul_f32 v[20:21], v[20:21], v[82:83] op_sel_hi:[1,0]
	v_pk_mul_f32 v[18:19], v[18:19], v[82:83] op_sel_hi:[1,0]
	v_pk_mul_f32 v[16:17], v[16:17], v[82:83] op_sel_hi:[1,0]
	v_mul_f32_e32 v231, v231, v82
	s_branch .LBB0_180

; #define MFMA32(a, b, c) __builtin_amdgcn_mfma_f32_32x32x16_bf16((a), (b), (c), 0, 0, 0)
; template <int NA, int MG>
; __device__ __forceinline__ void attn_pair_unit(const Params& p, int l, int u, LAS unsigned char* pl, int sub, int lane, int& g, const bool own0, const int nu) {
;     ...
;         else { const int krow = R0 + c; use = (krow >= ua) && (krow <= ub); }
;         if (!use) continue;
;         const unsigned slot = (unsigned)(g & 1) * VTILE;
;         bf16x8 kf[8];
;         asm volatile("ds_read_b128 %0, %8 offset:0\n\tds_read_b128 %1, %8 offset:32\n\tds_read_b128 %2, %8 offset:64\n\tds_read_b128 %3, %8 offset:96\n\t"
;                      "ds_read_b128 %4, %8 offset:128\n\tds_read_b128 %5, %8 offset:160\n\tds_read_b128 %6, %8 offset:192\n\tds_read_b128 %7, %8 offset:224\n\t"
;                      "s_waitcnt lgkmcnt(0)"
;                      : "=&v"(kf[0]), "=&v"(kf[1]), "=&v"(kf[2]), "=&v"(kf[3]), "=&v"(kf[4]), "=&v"(kf[5]), "=&v"(kf[6]), "=&v"(kf[7])
;                      : "v"(plw + slot + koff) : "memory");
;         f32x16 s;
; #pragma unroll
;         for (int i = 0; i < 16; ++i) s[i] = 0.f;
; #pragma unroll
;         for (int kk = 0; kk < 8; ++kk) s = MFMA32(kf[kk], qf[kk], s);
;         float cm = -1e30f;
; #pragma unroll
;         for (int i = 0; i < 16; ++i) {
;             const int kr = (i & 3) + 8 * (i >> 2) + 4 * h;
;             bool valid; float sv = s[i];
;             if (!NA) { const int dj = 32 * cl + kr - r; valid = (dj >= 0) && (dj <= 128); if (cl >= 1 && cl <= 3) valid = true; }
;             else { const int krow = R0 + c, kcol = kstart + kr;
;                 valid = (krow >= rsq) && (krow < rsq + 8) && (kcol >= csq) && (kcol < csq + 16);
;                 const int ro = clampi(krow - iq + 7, 0, 14), co = clampi(kcol - cq + 15, 0, 30); sv += bl[ro * 31 + co]; }
;             sv = valid ? sv : -1e30f; s[i] = sv; cm = fmaxf(cm, sv);
;         }
;         cm = fmaxf(cm, __shfl_xor(cm, 32));
.LBB0_189:
	s_andn2_b64 vcc, exec, s[62:63]
	s_cbranch_vccnz .LBB0_193
	s_bitcmp1_b32 s42, 0
	s_cselect_b32 s12, 0x2100, 0
	s_add_i32 s12, s12, s67
	v_add_u32_e32 v0, s12, v166
	ds_read_b128 v[2:5], v0 offset:0
	ds_read_b128 v[6:9], v0 offset:32
	ds_read_b128 v[10:13], v0 offset:64
	ds_read_b128 v[234:237], v0 offset:96
	ds_read_b128 v[238:241], v0 offset:128
	ds_read_b128 v[242:245], v0 offset:160
	ds_read_b128 v[246:249], v0 offset:192
	ds_read_b128 v[250:253], v0 offset:224
	s_waitcnt lgkmcnt(0)
	v_readlane_b32 s80, v254, 22
	v_mfma_f32_32x32x16_bf16 v[80:95], v[2:5], v[124:127], 0
	v_readlane_b32 s81, v254, 23
	v_mfma_f32_32x32x16_bf16 v[80:95], v[6:9], v[120:123], v[80:95]
	ds_read_b32 v0, v210 offset:33792
	ds_read_b32 v2, v211 offset:33792
	ds_read_b32 v3, v212 offset:33792
	ds_read_b32 v4, v213 offset:33792
	ds_read_b32 v5, v214 offset:33792
	ds_read_b32 v6, v215 offset:33792
	ds_read_b32 v7, v216 offset:33792
	ds_read_b32 v8, v217 offset:33792
	v_mfma_f32_32x32x16_bf16 v[80:95], v[10:13], v[116:119], v[80:95]
	v_mfma_f32_32x32x16_bf16 v[80:95], v[234:237], v[112:115], v[80:95]
	v_mfma_f32_32x32x16_bf16 v[80:95], v[238:241], v[104:107], v[80:95]
	v_mfma_f32_32x32x16_bf16 v[80:95], v[242:245], v[108:111], v[80:95]
	v_mfma_f32_32x32x16_bf16 v[80:95], v[246:249], v[100:103], v[80:95]
	ds_read_b32 v9, v218 offset:33792
	ds_read_b32 v10, v219 offset:33792
	ds_read_b32 v11, v220 offset:33792
	ds_read_b32 v12, v221 offset:33792
	ds_read_b32 v13, v222 offset:33792
	ds_read_b32 v14, v223 offset:33792
	ds_read_b32 v15, v224 offset:33792
	ds_read_b32 v100, v225 offset:33792
	v_mfma_f32_32x32x16_bf16 v[80:95], v[250:253], v[96:99], v[80:95]
	s_waitcnt lgkmcnt(0)
	s_nop 10
	v_add_f32_e32 v0, v80, v0
	v_cndmask_b32_e64 v80, v206, v0, s[80:81]
	v_readlane_b32 s80, v254, 24
	v_add_f32_e32 v2, v81, v2
	v_readlane_b32 s81, v254, 25
	v_add_f32_e32 v8, v87, v8
	v_add_f32_e32 v87, v94, v15
	v_cndmask_b32_e64 v15, v206, v2, s[80:81]
	v_readlane_b32 s80, v254, 26
	v_add_f32_e32 v3, v82, v3
	v_readlane_b32 s81, v254, 27
	v_add_f32_e32 v7, v86, v7
	v_add_f32_e32 v86, v93, v14
	v_cndmask_b32_e64 v14, v206, v3, s[80:81]
	v_readlane_b32 s80, v254, 28
	v_add_f32_e32 v4, v83, v4
	v_readlane_b32 s81, v254, 29
	v_add_f32_e32 v6, v85, v6
	v_add_f32_e32 v81, v88, v9
	v_add_f32_e32 v85, v92, v13
	v_cndmask_b32_e64 v13, v206, v4, s[80:81]
	v_readlane_b32 s80, v254, 30
	v_add_f32_e32 v5, v84, v5
	v_readlane_b32 s81, v254, 31
	v_cndmask_b32_e64 v9, v206, v8, s[18:19]
	v_cndmask_b32_e64 v8, v206, v81, s[20:21]
	v_max3_f32 v81, v80, s46, v15
	v_add_f32_e32 v83, v90, v11
	v_add_f32_e32 v84, v91, v12
	v_cndmask_b32_e64 v12, v206, v5, s[80:81]
	v_cndmask_b32_e64 v11, v206, v6, s[14:15]
	v_max3_f32 v81, v81, v14, v13
	v_add_f32_e32 v82, v89, v10
	v_cndmask_b32_e64 v10, v206, v7, s[16:17]
	v_max3_f32 v81, v81, v12, v11
	v_cndmask_b32_e64 v7, v206, v82, s[22:23]
	v_max3_f32 v81, v81, v10, v9
	v_cndmask_b32_e64 v6, v206, v83, s[24:25]
	v_cndmask_b32_e64 v5, v206, v84, s[26:27]
	v_max3_f32 v81, v81, v8, v7
	v_add_f32_e32 v88, v95, v100
	v_cndmask_b32_e64 v4, v206, v85, s[28:29]
	v_cndmask_b32_e64 v3, v206, v86, s[30:31]
	v_max3_f32 v81, v81, v6, v5
	v_cndmask_b32_e64 v2, v206, v87, s[34:35]
	v_cndmask_b32_e64 v0, v206, v88, s[36:37]
	v_max3_f32 v81, v81, v4, v3
	v_max3_f32 v81, v81, v2, v0
	v_mov_b32_e32 v82, v81
	v_mov_b32_e32 v84, v81
	s_nop 1
	v_permlane32_swap_b32_e32 v82, v84
	v_max_f32_e32 v81, v82, v84
	v_add_f32_e32 v82, 0x41000000, v232
	v_cmp_gt_f32_e32 vcc, v81, v82
	s_cbranch_vccz .LBB0_192
	v_max_f32_e32 v81, v81, v81
	v_max_f32_e32 v82, v232, v232
	v_max_f32_e32 v81, v82, v81
	v_sub_f32_e32 v82, v232, v81
	v_exp_f32_e32 v82, v82
	v_mov_b32_e32 v232, v81
	v_pk_mul_f32 v[78:79], v[78:79], v[82:83] op_sel_hi:[1,0]
	v_pk_mul_f32 v[76:77], v[76:77], v[82:83] op_sel_hi:[1,0]
	v_pk_mul_f32 v[74:75], v[74:75], v[82:83] op_sel_hi:[1,0]
	v_pk_mul_f32 v[72:73], v[72:73], v[82:83] op_sel_hi:[1,0]
	v_pk_mul_f32 v[70:71], v[70:71], v[82:83] op_sel_hi:[1,0]
	v_pk_mul_f32 v[68:69], v[68:69], v[82:83] op_sel_hi:[1,0]
	v_pk_mul_f32 v[66:67], v[66:67], v[82:83] op_sel_hi:[1,0]
	v_pk_mul_f32 v[64:65], v[64:65], v[82:83] op_sel_hi:[1,0]
	v_pk_mul_f32 v[62:63], v[62:63], v[82:83] op_sel_hi:[1,0]
	v_pk_mul_f32 v[60:61], v[60:61], v[82:83] op_sel_hi:[1,0]
	v_pk_mul_f32 v[58:59], v[58:59], v[82:83] op_sel_hi:[1,0]
	v_pk_mul_f32 v[56:57], v[56:57], v[82:83] op_sel_hi:[1,0]
	v_pk_mul_f32 v[54:55], v[54:55], v[82:83] op_sel_hi:[1,0]
	v_pk_mul_f32 v[52:53], v[52:53], v[82:83] op_sel_hi:[1,0]
	v_pk_mul_f32 v[50:51], v[50:51], v[82:83] op_sel_hi:[1,0]
	v_pk_mul_f32 v[48:49], v[48:49], v[82:83] op_sel_hi:[1,0]
	v_pk_mul_f32 v[46:47], v[46:47], v[82:83] op_sel_hi:[1,0]
	v_pk_mul_f32 v[44:45], v[44:45], v[82:83] op_sel_hi:[1,0]
	v_pk_mul_f32 v[42:43], v[42:43], v[82:83] op_sel_hi:[1,0]
	v_pk_mul_f32 v[40:41], v[40:41], v[82:83] op_sel_hi:[1,0]
	v_pk_mul_f32 v[38:39], v[38:39], v[82:83] op_sel_hi:[1,0]
	v_pk_mul_f32 v[36:37], v[36:37], v[82:83] op_sel_hi:[1,0]
	v_pk_mul_f32 v[34:35], v[34:35], v[82:83] op_sel_hi:[1,0]
	v_pk_mul_f32 v[32:33], v[32:33], v[82:83] op_sel_hi:[1,0]
	v_pk_mul_f32 v[30:31], v[30:31], v[82:83] op_sel_hi:[1,0]
	v_pk_mul_f32 v[28:29], v[28:29], v[82:83] op_sel_hi:[1,0]
	v_pk_mul_f32 v[26:27], v[26:27], v[82:83] op_sel_hi:[1,0]
	v_pk_mul_f32 v[24:25], v[24:25], v[82:83] op_sel_hi:[1,0]
	v_pk_mul_f32 v[22:23], v[22:23], v[82:83] op_sel_hi:[1,0]
	v_pk_mul_f32 v[20:21], v[20:21], v[82:83] op_sel_hi:[1,0]
	v_pk_mul_f32 v[18:19], v[18:19], v[82:83] op_sel_hi:[1,0]
	v_pk_mul_f32 v[16:17], v[16:17], v[82:83] op_sel_hi:[1,0]
	v_mul_f32_e32 v231, v231, v82

; template <int NA, int MG>
; __device__ __forceinline__ void attn_pair_unit(const Params& p, int l, int u, LAS unsigned char* pl, int sub, int lane, int& g, const bool own0, const int nu) {
;     ...
;         if (c + 1 < NS) { if (ATT_CVALID(c + 1)) ATT_DMA(c + 1, (g + 1) & 1); }
;         else if (nu >= 0) attn_prefetch0<NA>(p, nu, sub, lane, dl + ((g + 1) & 1) * VTILE);
;         bool use;
;         int cl = 0;
;         if (!NA) { cl = c - sub; use = ATT_CVALID(c) && cl >= 0 && cl <= 4; }
;         else { const int krow = R0 + c; use = (krow >= ua) && (krow <= ub); }
;         if (!use) continue;
;         const unsigned slot = (unsigned)(g & 1) * VTILE;
;         bf16x8 kf[8];
;         asm volatile("ds_read_b128 %0, %8 offset:0\n\tds_read_b128 %1, %8 offset:32\n\tds_read_b128 %2, %8 offset:64\n\tds_read_b128 %3, %8 offset:96\n\t"
;                      "ds_read_b128 %4, %8 offset:128\n\tds_read_b128 %5, %8 offset:160\n\tds_read_b128 %6, %8 offset:192\n\tds_read_b128 %7, %8 offset:224\n\t"
;                      "s_waitcnt lgkmcnt(0)"
;                      : "=&v"(kf[0]), "=&v"(kf[1]), "=&v"(kf[2]), "=&v"(kf[3]), "=&v"(kf[4]), "=&v"(kf[5]), "=&v"(kf[6]), "=&v"(kf[7])
;                      : "v"(plw + slot + koff) : "memory");
;         f32x16 s;
; #pragma unroll
;         for (int i = 0; i < 16; ++i) s[i] = 0.f;
; #pragma unroll
;         for (int kk = 0; kk < 8; ++kk) s = MFMA32(kf[kk], qf[kk], s);
;         float cm = -1e30f;
; #pragma unroll
;         for (int i = 0; i < 16; ++i) {
;             const int kr = (i & 3) + 8 * (i >> 2) + 4 * h;
;             bool valid; float sv = s[i];
;             if (!NA) { const int dj = 32 * cl + kr - r; valid = (dj >= 0) && (dj <= 128); if (cl >= 1 && cl <= 3) valid = true; }
;             else { const int krow = R0 + c, kcol = kstart + kr;
;                 valid = (krow >= rsq) && (krow < rsq + 8) && (kcol >= csq) && (kcol < csq + 16);
;                 const int ro = clampi(krow - iq + 7, 0, 14), co = clampi(kcol - cq + 15, 0, 30); sv += bl[ro * 31 + co]; }
;             sv = valid ? sv : -1e30f; s[i] = sv; cm = fmaxf(cm, sv);
;         }
;         cm = fmaxf(cm, __shfl_xor(cm, 32));
;         if (__builtin_amdgcn_ballot_w64(cm > m_run + 8.0f) != 0ull) {
;             const float m_new = fmaxf(m_run, cm), alpha = __builtin_amdgcn_exp2f(m_run - m_new);
;             l_run *= alpha; m_run = m_new;
; #pragma unroll
.LBB0_207:
	s_sub_i32 s50, s74, 64
	s_cmp_lt_i32 s50, 0
	s_cbranch_scc1 .LBB0_212
	s_cmp_lt_i32 s50, s45
	s_cselect_b64 s[74:75], -1, 0
	s_cmp_lt_u32 s94, 5
	s_cselect_b64 s[96:97], -1, 0
	s_and_b64 s[74:75], s[74:75], s[96:97]
	s_andn2_b64 vcc, exec, s[74:75]
	s_cbranch_vccnz .LBB0_212
	s_bitcmp1_b32 s84, 0
	s_cselect_b32 s50, 0x2100, 0
	s_add_i32 s50, s50, s0
	v_add_u32_e32 v0, s50, v143
	ds_read_b128 v[2:5], v0 offset:0
	ds_read_b128 v[6:9], v0 offset:32
	ds_read_b128 v[10:13], v0 offset:64
	ds_read_b128 v[180:183], v0 offset:96
	ds_read_b128 v[184:187], v0 offset:128
	ds_read_b128 v[188:191], v0 offset:160
	ds_read_b128 v[192:195], v0 offset:192
	ds_read_b128 v[196:199], v0 offset:224
	s_waitcnt lgkmcnt(0)
	s_add_i32 s74, s94, -1
	v_mfma_f32_32x32x16_bf16 v[80:95], v[2:5], v[124:127], 0
	v_add_u32_e32 v139, s93, v176
	s_cmp_lt_u32 s74, 3
	s_cselect_b64 s[74:75], -1, 0
	v_cmp_gt_u32_e32 vcc, s33, v139
	s_or_b64 vcc, s[74:75], vcc
	v_add_u32_e32 v2, 1, v139
	v_add_u32_e32 v3, 2, v139
	v_mfma_f32_32x32x16_bf16 v[80:95], v[6:9], v[120:123], v[80:95]
	v_add_u32_e32 v4, 3, v139
	v_add_u32_e32 v6, 9, v139
	v_add_u32_e32 v9, 11, v139
	v_add_u32_e32 v14, 25, v139
	v_mfma_f32_32x32x16_bf16 v[80:95], v[10:13], v[116:119], v[80:95]
	v_add_u32_e32 v12, 19, v139
	v_mfma_f32_32x32x16_bf16 v[80:95], v[180:183], v[112:115], v[80:95]
	v_mfma_f32_32x32x16_bf16 v[80:95], v[184:187], v[108:111], v[80:95]
	v_mfma_f32_32x32x16_bf16 v[80:95], v[188:191], v[104:107], v[80:95]
	v_mfma_f32_32x32x16_bf16 v[80:95], v[192:195], v[100:103], v[80:95]
	v_mfma_f32_32x32x16_bf16 v[80:95], v[196:199], v[96:99], v[80:95]
	s_nop 11
	v_cndmask_b32_e32 v0, v206, v80, vcc
	v_cmp_gt_u32_e32 vcc, s33, v2
	s_or_b64 vcc, s[74:75], vcc
	v_add_u32_e32 v80, 27, v139
	v_cndmask_b32_e32 v2, v206, v81, vcc
	v_cmp_gt_u32_e32 vcc, s33, v3
	s_or_b64 vcc, s[74:75], vcc
	v_max3_f32 v5, v0, s46, v2
	v_cndmask_b32_e32 v3, v206, v82, vcc
	v_cmp_gt_u32_e32 vcc, s33, v4
	s_or_b64 vcc, s[74:75], vcc
	v_xor_b32_e32 v82, 32, v204
	v_cndmask_b32_e32 v4, v206, v83, vcc
	v_max3_f32 v7, v5, v3, v4
	v_add_u32_e32 v5, 8, v139
	v_cmp_gt_u32_e32 vcc, s33, v5
	s_or_b64 vcc, s[74:75], vcc
	v_and_b32_e32 v83, 64, v204
	v_cndmask_b32_e32 v5, v206, v84, vcc
	v_cmp_gt_u32_e32 vcc, s33, v6
	s_or_b64 vcc, s[74:75], vcc
	v_add_u32_e32 v83, 64, v83
	v_cndmask_b32_e32 v6, v206, v85, vcc
	v_max3_f32 v8, v7, v5, v6
	v_add_u32_e32 v7, 10, v139
	v_cmp_gt_u32_e32 vcc, s33, v7
	s_or_b64 vcc, s[74:75], vcc
	s_nop 0
	v_cndmask_b32_e32 v7, v206, v86, vcc
	v_cmp_gt_u32_e32 vcc, s33, v9
	s_or_b64 vcc, s[74:75], vcc
	v_add_u32_e32 v9, 17, v139
	v_cndmask_b32_e32 v10, v206, v87, vcc
	v_max3_f32 v11, v8, v7, v10
	v_add_u32_e32 v8, 16, v139
	v_cmp_gt_u32_e32 vcc, s33, v8
	s_or_b64 vcc, s[74:75], vcc
	s_nop 0
	v_cndmask_b32_e32 v8, v206, v88, vcc
	v_cmp_gt_u32_e32 vcc, s33, v9
	s_or_b64 vcc, s[74:75], vcc
	s_nop 0
	v_cndmask_b32_e32 v9, v206, v89, vcc
	v_max3_f32 v13, v11, v8, v9
	v_add_u32_e32 v11, 18, v139
	v_cmp_gt_u32_e32 vcc, s33, v11
	s_or_b64 vcc, s[74:75], vcc
	s_nop 0
	v_cndmask_b32_e32 v11, v206, v90, vcc
	v_cmp_gt_u32_e32 vcc, s33, v12
	s_or_b64 vcc, s[74:75], vcc
	s_nop 0
	v_cndmask_b32_e32 v12, v206, v91, vcc
	v_max3_f32 v15, v13, v11, v12
	v_add_u32_e32 v13, 24, v139
	v_cmp_gt_u32_e32 vcc, s33, v13
	s_or_b64 vcc, s[74:75], vcc
	s_nop 0
	v_cndmask_b32_e32 v13, v206, v92, vcc
	v_cmp_gt_u32_e32 vcc, s33, v14
	s_or_b64 vcc, s[74:75], vcc
	s_nop 0
	v_cndmask_b32_e32 v14, v206, v93, vcc
	v_max3_f32 v81, v15, v13, v14
	v_add_u32_e32 v15, 26, v139
	v_cmp_gt_u32_e32 vcc, s33, v15
	s_or_b64 vcc, s[74:75], vcc
	s_nop 0
	v_cndmask_b32_e32 v15, v206, v94, vcc
	v_cmp_gt_u32_e32 vcc, s33, v80
	s_or_b64 vcc, s[74:75], vcc
	s_nop 0
	v_cndmask_b32_e32 v80, v206, v95, vcc
	v_cmp_lt_i32_e32 vcc, v82, v83
	v_max3_f32 v81, v81, v15, v80
	s_nop 0
	v_mov_b32_e32 v82, v81
	v_mov_b32_e32 v240, v81
	s_nop 1
	v_permlane32_swap_b32_e32 v82, v240
	v_max_f32_e32 v81, v82, v240
	v_add_f32_e32 v82, 0x41000000, v138
	v_cmp_gt_f32_e32 vcc, v81, v82
	s_cbranch_vccz .LBB0_211
	v_max_f32_e32 v81, v81, v81
	v_max_f32_e32 v82, v138, v138
	v_max_f32_e32 v81, v82, v81
	v_sub_f32_e32 v82, v138, v81
	v_exp_f32_e32 v82, v82
	v_mov_b32_e32 v138, v81
	v_pk_mul_f32 v[78:79], v[78:79], v[82:83] op_sel_hi:[1,0]
	v_pk_mul_f32 v[76:77], v[76:77], v[82:83] op_sel_hi:[1,0]
	v_pk_mul_f32 v[74:75], v[74:75], v[82:83] op_sel_hi:[1,0]
	v_pk_mul_f32 v[72:73], v[72:73], v[82:83] op_sel_hi:[1,0]
	v_pk_mul_f32 v[70:71], v[70:71], v[82:83] op_sel_hi:[1,0]
	v_pk_mul_f32 v[68:69], v[68:69], v[82:83] op_sel_hi:[1,0]
	v_pk_mul_f32 v[66:67], v[66:67], v[82:83] op_sel_hi:[1,0]
	v_pk_mul_f32 v[64:65], v[64:65], v[82:83] op_sel_hi:[1,0]
	v_pk_mul_f32 v[62:63], v[62:63], v[82:83] op_sel_hi:[1,0]
	v_pk_mul_f32 v[60:61], v[60:61], v[82:83] op_sel_hi:[1,0]
	v_pk_mul_f32 v[58:59], v[58:59], v[82:83] op_sel_hi:[1,0]
	v_pk_mul_f32 v[56:57], v[56:57], v[82:83] op_sel_hi:[1,0]
	v_pk_mul_f32 v[54:55], v[54:55], v[82:83] op_sel_hi:[1,0]
	v_pk_mul_f32 v[52:53], v[52:53], v[82:83] op_sel_hi:[1,0]
	v_pk_mul_f32 v[50:51], v[50:51], v[82:83] op_sel_hi:[1,0]
	v_pk_mul_f32 v[48:49], v[48:49], v[82:83] op_sel_hi:[1,0]
	v_pk_mul_f32 v[46:47], v[46:47], v[82:83] op_sel_hi:[1,0]
	v_pk_mul_f32 v[44:45], v[44:45], v[82:83] op_sel_hi:[1,0]
	v_pk_mul_f32 v[42:43], v[42:43], v[82:83] op_sel_hi:[1,0]
	v_pk_mul_f32 v[40:41], v[40:41], v[82:83] op_sel_hi:[1,0]
	v_pk_mul_f32 v[38:39], v[38:39], v[82:83] op_sel_hi:[1,0]
	v_pk_mul_f32 v[36:37], v[36:37], v[82:83] op_sel_hi:[1,0]
	v_pk_mul_f32 v[34:35], v[34:35], v[82:83] op_sel_hi:[1,0]
	v_pk_mul_f32 v[32:33], v[32:33], v[82:83] op_sel_hi:[1,0]
	v_pk_mul_f32 v[30:31], v[30:31], v[82:83] op_sel_hi:[1,0]
	v_pk_mul_f32 v[28:29], v[28:29], v[82:83] op_sel_hi:[1,0]
	v_pk_mul_f32 v[26:27], v[26:27], v[82:83] op_sel_hi:[1,0]
	v_pk_mul_f32 v[24:25], v[24:25], v[82:83] op_sel_hi:[1,0]
	v_pk_mul_f32 v[22:23], v[22:23], v[82:83] op_sel_hi:[1,0]
	v_pk_mul_f32 v[20:21], v[20:21], v[82:83] op_sel_hi:[1,0]
	v_pk_mul_f32 v[18:19], v[18:19], v[82:83] op_sel_hi:[1,0]
	v_pk_mul_f32 v[16:17], v[16:17], v[82:83] op_sel_hi:[1,0]
	v_mul_f32_e32 v135, v135, v82

; template <int NA, int MG>
; __device__ __forceinline__ void attn_pair_unit(const Params& p, int l, int u, LAS unsigned char* pl, int sub, int lane, int& g, const bool own0, const int nu) {
;     ...
;         if (c + 1 < NS) { if (ATT_CVALID(c + 1)) ATT_DMA(c + 1, (g + 1) & 1); }
;         else if (nu >= 0) attn_prefetch0<NA>(p, nu, sub, lane, dl + ((g + 1) & 1) * VTILE);
;         bool use;
;         int cl = 0;
;         if (!NA) { cl = c - sub; use = ATT_CVALID(c) && cl >= 0 && cl <= 4; }
;         else { const int krow = R0 + c; use = (krow >= ua) && (krow <= ub); }
;         if (!use) continue;
;         const unsigned slot = (unsigned)(g & 1) * VTILE;
;         bf16x8 kf[8];
;         asm volatile("ds_read_b128 %0, %8 offset:0\n\tds_read_b128 %1, %8 offset:32\n\tds_read_b128 %2, %8 offset:64\n\tds_read_b128 %3, %8 offset:96\n\t"
;                      "ds_read_b128 %4, %8 offset:128\n\tds_read_b128 %5, %8 offset:160\n\tds_read_b128 %6, %8 offset:192\n\tds_read_b128 %7, %8 offset:224\n\t"
;                      "s_waitcnt lgkmcnt(0)"
;                      : "=&v"(kf[0]), "=&v"(kf[1]), "=&v"(kf[2]), "=&v"(kf[3]), "=&v"(kf[4]), "=&v"(kf[5]), "=&v"(kf[6]), "=&v"(kf[7])
;                      : "v"(plw + slot + koff) : "memory");
;         f32x16 s;
; #pragma unroll
;         for (int i = 0; i < 16; ++i) s[i] = 0.f;
; #pragma unroll
;         for (int kk = 0; kk < 8; ++kk) s = MFMA32(kf[kk], qf[kk], s);
;         float cm = -1e30f;
; #pragma unroll
;         for (int i = 0; i < 16; ++i) {
;             const int kr = (i & 3) + 8 * (i >> 2) + 4 * h;
;             bool valid; float sv = s[i];
;             if (!NA) { const int dj = 32 * cl + kr - r; valid = (dj >= 0) && (dj <= 128); if (cl >= 1 && cl <= 3) valid = true; }
;             else { const int krow = R0 + c, kcol = kstart + kr;
;                 valid = (krow >= rsq) && (krow < rsq + 8) && (kcol >= csq) && (kcol < csq + 16);
;                 const int ro = clampi(krow - iq + 7, 0, 14), co = clampi(kcol - cq + 15, 0, 30); sv += bl[ro * 31 + co]; }
;             sv = valid ? sv : -1e30f; s[i] = sv; cm = fmaxf(cm, sv);
;         }
;         cm = fmaxf(cm, __shfl_xor(cm, 32));
;         if (__builtin_amdgcn_ballot_w64(cm > m_run + 8.0f) != 0ull) {
;             const float m_new = fmaxf(m_run, cm), alpha = __builtin_amdgcn_exp2f(m_run - m_new);
;             l_run *= alpha; m_run = m_new;
; #pragma unroll
.LBB0_216:
	s_add_i32 s50, s90, 0x60
	s_cmp_lt_u32 s50, s45
	s_cselect_b64 s[52:53], -1, 0
	s_and_b64 s[52:53], s[52:53], s[42:43]
	s_andn2_b64 vcc, exec, s[52:53]
	s_cbranch_vccnz .LBB0_220
	s_bitcmp1_b32 s95, 0
	s_cselect_b32 s45, 0x2100, 0
	s_add_i32 s45, s45, s0
	v_add_u32_e32 v0, s45, v143
	ds_read_b128 v[2:5], v0 offset:0
	ds_read_b128 v[6:9], v0 offset:32
	ds_read_b128 v[10:13], v0 offset:64
	ds_read_b128 v[180:183], v0 offset:96
	ds_read_b128 v[184:187], v0 offset:128
	ds_read_b128 v[188:191], v0 offset:160
	ds_read_b128 v[192:195], v0 offset:192
	ds_read_b128 v[196:199], v0 offset:224
	s_waitcnt lgkmcnt(0)
	v_xor_b32_e32 v0, 32, v204
	v_mfma_f32_32x32x16_bf16 v[80:95], v[2:5], v[124:127], 0
	v_and_b32_e32 v2, 64, v204
	v_add_u32_e32 v2, 64, v2
	v_cmp_lt_i32_e32 vcc, v0, v2
	s_nop 1
	v_cndmask_b32_e32 v0, v204, v0, vcc
	v_mfma_f32_32x32x16_bf16 v[80:95], v[6:9], v[120:123], v[80:95]
	v_mfma_f32_32x32x16_bf16 v[80:95], v[10:13], v[116:119], v[80:95]
	v_mfma_f32_32x32x16_bf16 v[80:95], v[180:183], v[112:115], v[80:95]
	v_mfma_f32_32x32x16_bf16 v[80:95], v[184:187], v[108:111], v[80:95]
	v_mfma_f32_32x32x16_bf16 v[80:95], v[188:191], v[104:107], v[80:95]
	v_mfma_f32_32x32x16_bf16 v[80:95], v[192:195], v[100:103], v[80:95]
	v_lshlrev_b32_e32 v100, 2, v0
	v_mfma_f32_32x32x16_bf16 v[80:95], v[196:199], v[96:99], v[80:95]
	s_nop 11
	v_cndmask_b32_e64 v80, v206, v80, s[4:5]
	v_cndmask_b32_e64 v15, v206, v81, s[6:7]
	v_cndmask_b32_e64 v14, v206, v82, s[8:9]
	v_cndmask_b32_e64 v13, v206, v83, s[10:11]
	v_max3_f32 v81, v80, s46, v15
	v_cndmask_b32_e64 v12, v206, v84, s[12:13]
	v_cndmask_b32_e64 v11, v206, v85, s[14:15]
	v_max3_f32 v81, v81, v14, v13
	v_cndmask_b32_e64 v10, v206, v86, s[16:17]
	v_cndmask_b32_e64 v9, v206, v87, s[18:19]
	v_max3_f32 v81, v81, v12, v11
	v_cndmask_b32_e64 v8, v206, v88, s[20:21]
	v_cndmask_b32_e64 v7, v206, v89, s[22:23]
	v_max3_f32 v81, v81, v10, v9
	v_cndmask_b32_e64 v6, v206, v90, s[24:25]
	v_cndmask_b32_e64 v5, v206, v91, s[26:27]
	v_max3_f32 v81, v81, v8, v7
	v_cndmask_b32_e64 v4, v206, v92, s[28:29]
	v_cndmask_b32_e64 v3, v206, v93, s[30:31]
	v_max3_f32 v81, v81, v6, v5
	v_cndmask_b32_e64 v2, v206, v94, s[34:35]
	v_cndmask_b32_e64 v0, v206, v95, s[36:37]
	v_max3_f32 v81, v81, v4, v3
	v_max3_f32 v81, v81, v2, v0
	v_mov_b32_e32 v82, v81
	v_mov_b32_e32 v240, v81
	s_nop 1
	v_permlane32_swap_b32_e32 v82, v240
	v_max_f32_e32 v81, v82, v240
	v_add_f32_e32 v82, 0x41000000, v138
	v_cmp_gt_f32_e32 vcc, v81, v82
	s_cbranch_vccz .LBB0_219
	v_max_f32_e32 v81, v81, v81
	v_max_f32_e32 v82, v138, v138
	v_max_f32_e32 v81, v82, v81
	v_sub_f32_e32 v82, v138, v81
	v_exp_f32_e32 v82, v82
	v_mov_b32_e32 v138, v81
	v_pk_mul_f32 v[78:79], v[78:79], v[82:83] op_sel_hi:[1,0]
	v_pk_mul_f32 v[76:77], v[76:77], v[82:83] op_sel_hi:[1,0]
	v_pk_mul_f32 v[74:75], v[74:75], v[82:83] op_sel_hi:[1,0]
	v_pk_mul_f32 v[72:73], v[72:73], v[82:83] op_sel_hi:[1,0]
	v_pk_mul_f32 v[70:71], v[70:71], v[82:83] op_sel_hi:[1,0]
	v_pk_mul_f32 v[68:69], v[68:69], v[82:83] op_sel_hi:[1,0]
	v_pk_mul_f32 v[66:67], v[66:67], v[82:83] op_sel_hi:[1,0]
	v_pk_mul_f32 v[64:65], v[64:65], v[82:83] op_sel_hi:[1,0]
	v_pk_mul_f32 v[62:63], v[62:63], v[82:83] op_sel_hi:[1,0]
	v_pk_mul_f32 v[60:61], v[60:61], v[82:83] op_sel_hi:[1,0]
	v_pk_mul_f32 v[58:59], v[58:59], v[82:83] op_sel_hi:[1,0]
	v_pk_mul_f32 v[56:57], v[56:57], v[82:83] op_sel_hi:[1,0]
	v_pk_mul_f32 v[54:55], v[54:55], v[82:83] op_sel_hi:[1,0]
	v_pk_mul_f32 v[52:53], v[52:53], v[82:83] op_sel_hi:[1,0]
	v_pk_mul_f32 v[50:51], v[50:51], v[82:83] op_sel_hi:[1,0]
	v_pk_mul_f32 v[48:49], v[48:49], v[82:83] op_sel_hi:[1,0]
	v_pk_mul_f32 v[46:47], v[46:47], v[82:83] op_sel_hi:[1,0]
	v_pk_mul_f32 v[44:45], v[44:45], v[82:83] op_sel_hi:[1,0]
	v_pk_mul_f32 v[42:43], v[42:43], v[82:83] op_sel_hi:[1,0]
	v_pk_mul_f32 v[40:41], v[40:41], v[82:83] op_sel_hi:[1,0]
	v_pk_mul_f32 v[38:39], v[38:39], v[82:83] op_sel_hi:[1,0]
	v_pk_mul_f32 v[36:37], v[36:37], v[82:83] op_sel_hi:[1,0]
	v_pk_mul_f32 v[34:35], v[34:35], v[82:83] op_sel_hi:[1,0]
	v_pk_mul_f32 v[32:33], v[32:33], v[82:83] op_sel_hi:[1,0]
	v_pk_mul_f32 v[30:31], v[30:31], v[82:83] op_sel_hi:[1,0]
	v_pk_mul_f32 v[28:29], v[28:29], v[82:83] op_sel_hi:[1,0]
	v_pk_mul_f32 v[26:27], v[26:27], v[82:83] op_sel_hi:[1,0]
	v_pk_mul_f32 v[24:25], v[24:25], v[82:83] op_sel_hi:[1,0]
	v_pk_mul_f32 v[22:23], v[22:23], v[82:83] op_sel_hi:[1,0]
	v_pk_mul_f32 v[20:21], v[20:21], v[82:83] op_sel_hi:[1,0]
	v_pk_mul_f32 v[18:19], v[18:19], v[82:83] op_sel_hi:[1,0]
	v_pk_mul_f32 v[16:17], v[16:17], v[82:83] op_sel_hi:[1,0]
	v_mul_f32_e32 v135, v135, v82
